# grid barrier: waiting workgroups poll the cross-XCD arrival counter itself (released when it reaches (gen+1)*nx) instead of the generation word the last leader bumps afterwards
# speedup vs baseline: 1.0352x; 1.0178x over previous
; __device__ __forceinline__ unsigned xb_ld(unsigned* p)              { return __hip_atomic_load(p, __ATOMIC_RELAXED, __HIP_MEMORY_SCOPE_AGENT); }
; __device__ __forceinline__ unsigned xb_add(unsigned* p, unsigned v) { return __hip_atomic_fetch_add(p, v, __ATOMIC_RELAXED, __HIP_MEMORY_SCOPE_AGENT); }
; #define XB_SPIN(cond, bar) do { unsigned _sp = 0; while (cond) { __builtin_amdgcn_s_sleep(1); \
;     if ((++_sp & 255u) == 0u) { if (xb_ld(&(bar)[XB_TMO])) break; if (_sp > XB_SPIN_CAP) { atomicAdd(&(bar)[XB_TMO], 1u); break; } } } } while (0)
; __device__ __forceinline__ void xcd_barrier(const XcdBarrier& b) {
;     ...
;         const unsigned old = xb_add(&bar[XB_XSUB(b.x)], 1u);
;         const unsigned gen = old / nloc;
;         if (old + 1u == (gen + 1u) * nloc) {
;             __builtin_amdgcn_fence(__ATOMIC_RELEASE, "agent");
;             asm volatile("s_waitcnt vmcnt(0)" ::: "memory");
;             const unsigned og = xb_add(&bar[XB_TOP], 1u);
;             const unsigned tg = og / nx;
;             if (og + 1u == (tg + 1u) * nx) xb_add(&bar[XB_TOPGEN], 1u);
;             else XB_SPIN(xb_ld(&bar[XB_TOPGEN]) == tg, bar);
;             __builtin_amdgcn_fence(__ATOMIC_ACQUIRE, "agent");
;             xb_add(&bar[XB_XGEN(b.x)], 1u);
;             asm volatile("s_waitcnt vmcnt(0)" ::: "memory");
;         } else {
;             XB_SPIN(xb_ld(&bar[XB_XGEN(b.x)]) == gen, bar);
;             __builtin_amdgcn_fence(__ATOMIC_ACQUIRE, "agent");
.LBB0_72:
	s_or_b64 exec, exec, s[2:3]
	v_cvt_f32_u32_e32 v4, v2
	s_waitcnt vmcnt(0)
	v_readfirstlane_b32 s2, v3
	v_sub_u32_e32 v3, 0, v2
	v_rcp_iflag_f32_e32 v4, v4
	v_add_u32_e32 v5, s2, v1
	v_mul_f32_e32 v4, 0x4f7ffffe, v4
	v_cvt_u32_f32_e32 v4, v4
	v_mul_lo_u32 v1, v3, v4
	v_mul_hi_u32 v1, v4, v1
	v_add_u32_e32 v1, v4, v1
	v_mul_hi_u32 v1, v5, v1
	v_mul_lo_u32 v3, v1, v2
	v_sub_u32_e32 v3, v5, v3
	v_add_u32_e32 v4, 1, v1
	v_cmp_ge_u32_e32 vcc, v3, v2
	s_nop 1
	v_cndmask_b32_e32 v1, v1, v4, vcc
	v_sub_u32_e32 v4, v3, v2
	v_cndmask_b32_e32 v3, v3, v4, vcc
	v_add_u32_e32 v4, 1, v1
	v_cmp_ge_u32_e32 vcc, v3, v2
	v_add_u32_e32 v3, 1, v5
	s_nop 0
	v_cndmask_b32_e32 v1, v1, v4, vcc
	v_mul_lo_u32 v4, v2, v1
	v_add_u32_e32 v2, v4, v2
	v_cmp_ne_u32_e32 vcc, v3, v2
	s_and_saveexec_b64 s[2:3], vcc
	s_xor_b64 s[2:3], exec, s[2:3]
	s_cbranch_execz .LBB0_86
	v_readlane_b32 s4, v253, 0
	s_waitcnt lgkmcnt(0)
	v_mul_lo_u32 v5, v1, v0
	v_add_u32_e32 v5, v5, v0
	v_mov_b32_e32 v0, 0
	v_readlane_b32 s5, v253, 1
	s_nop 4
	buffer_inv sc1
	global_load_dword v2, v0, s[4:5] sc1
	s_waitcnt vmcnt(0)
	v_cmp_gt_u32_e32 vcc, v5, v2
	s_and_saveexec_b64 s[4:5], vcc
	s_cbranch_execz .LBB0_85
	s_mov_b32 s15, 1
	s_mov_b64 s[6:7], 0
	s_branch .LBB0_76

; __device__ __forceinline__ unsigned xb_ld(unsigned* p)              { return __hip_atomic_load(p, __ATOMIC_RELAXED, __HIP_MEMORY_SCOPE_AGENT); }
; #define XB_SPIN(cond, bar) do { unsigned _sp = 0; while (cond) { __builtin_amdgcn_s_sleep(1); \
;     if ((++_sp & 255u) == 0u) { if (xb_ld(&(bar)[XB_TMO])) break; if (_sp > XB_SPIN_CAP) { atomicAdd(&(bar)[XB_TMO], 1u); break; } } } } while (0)
; __device__ __forceinline__ void xcd_barrier(const XcdBarrier& b) {
;     ...
;             XB_SPIN(xb_ld(&bar[XB_XGEN(b.x)]) == gen, bar);
.LBB0_80:
	v_readlane_b32 s10, v253, 0
	v_readlane_b32 s11, v253, 1
	s_add_i32 s15, s15, 1
	s_mov_b64 s[12:13], -1
	s_nop 2
	global_load_dword v2, v0, s[10:11] sc1
	s_waitcnt vmcnt(0)
	v_cmp_le_u32_e32 vcc, v5, v2
	s_orn2_b64 s[10:11], vcc, exec
	s_branch .LBB0_75

; __device__ __forceinline__ unsigned xb_ld(unsigned* p)              { return __hip_atomic_load(p, __ATOMIC_RELAXED, __HIP_MEMORY_SCOPE_AGENT); }
; __device__ __forceinline__ unsigned xb_add(unsigned* p, unsigned v) { return __hip_atomic_fetch_add(p, v, __ATOMIC_RELAXED, __HIP_MEMORY_SCOPE_AGENT); }
; #define XB_SPIN(cond, bar) do { unsigned _sp = 0; while (cond) { __builtin_amdgcn_s_sleep(1); \
;     if ((++_sp & 255u) == 0u) { if (xb_ld(&(bar)[XB_TMO])) break; if (_sp > XB_SPIN_CAP) { atomicAdd(&(bar)[XB_TMO], 1u); break; } } } } while (0)
; __device__ __forceinline__ void xcd_barrier(const XcdBarrier& b) {
;     ...
;             const unsigned og = xb_add(&bar[XB_TOP], 1u);
;             const unsigned tg = og / nx;
;             if (og + 1u == (tg + 1u) * nx) xb_add(&bar[XB_TOPGEN], 1u);
;             else XB_SPIN(xb_ld(&bar[XB_TOPGEN]) == tg, bar);
.LBB0_89:
	s_or_b64 exec, exec, s[4:5]
	v_cvt_f32_u32_e32 v3, v0
	s_waitcnt vmcnt(0)
	v_readfirstlane_b32 s2, v2
	s_mov_b64 s[4:5], -1
	v_rcp_iflag_f32_e32 v3, v3
	v_add_u32_e32 v1, s2, v1
	v_add_u32_e32 v4, 1, v1
	v_readlane_b32 s2, v253, 2
	v_mul_f32_e32 v2, 0x4f7ffffe, v3
	v_cvt_u32_f32_e32 v2, v2
	v_sub_u32_e32 v3, 0, v0
	v_readlane_b32 s3, v253, 3
	v_mul_lo_u32 v3, v3, v2
	v_mul_hi_u32 v3, v2, v3
	v_add_u32_e32 v2, v2, v3
	v_mul_hi_u32 v2, v1, v2
	v_mul_lo_u32 v3, v2, v0
	v_sub_u32_e32 v1, v1, v3
	v_add_u32_e32 v5, 1, v2
	v_cmp_ge_u32_e32 vcc, v1, v0
	v_sub_u32_e32 v3, v1, v0
	s_nop 0
	v_cndmask_b32_e32 v2, v2, v5, vcc
	v_cndmask_b32_e32 v1, v1, v3, vcc
	v_add_u32_e32 v3, 1, v2
	v_cmp_ge_u32_e32 vcc, v1, v0
	s_nop 1
	v_cndmask_b32_e32 v2, v2, v3, vcc
	v_mul_lo_u32 v1, v0, v2
	v_add_u32_e32 v0, v1, v0
	v_cmp_ne_u32_e32 vcc, v4, v0
	v_mov_b32_e32 v5, v0
	v_mov_b64_e32 v[0:1], s[2:3]
	s_and_saveexec_b64 s[2:3], vcc
	s_cbranch_execz .LBB0_101
	v_readlane_b32 s4, v253, 0
	v_mov_b32_e32 v0, 0
	v_readlane_b32 s5, v253, 1
	s_mov_b64 s[6:7], 0
	s_nop 3
	global_load_dword v1, v0, s[4:5] sc1
	s_waitcnt vmcnt(0)
	v_cmp_gt_u32_e32 vcc, v5, v1
	s_and_saveexec_b64 s[4:5], vcc
	s_cbranch_execz .LBB0_100
	s_mov_b32 s15, 1
	s_branch .LBB0_93

; __device__ __forceinline__ unsigned xb_ld(unsigned* p)              { return __hip_atomic_load(p, __ATOMIC_RELAXED, __HIP_MEMORY_SCOPE_AGENT); }
; #define XB_SPIN(cond, bar) do { unsigned _sp = 0; while (cond) { __builtin_amdgcn_s_sleep(1); \
;     if ((++_sp & 255u) == 0u) { if (xb_ld(&(bar)[XB_TMO])) break; if (_sp > XB_SPIN_CAP) { atomicAdd(&(bar)[XB_TMO], 1u); break; } } } } while (0)
; __device__ __forceinline__ void xcd_barrier(const XcdBarrier& b) {
;     ...
;             else XB_SPIN(xb_ld(&bar[XB_TOPGEN]) == tg, bar);
.LBB0_97:
	v_readlane_b32 s10, v253, 0
	v_readlane_b32 s11, v253, 1
	s_add_i32 s15, s15, 1
	s_nop 3
	global_load_dword v1, v0, s[10:11] sc1
	s_mov_b64 s[10:11], -1
	s_waitcnt vmcnt(0)
	v_cmp_le_u32_e32 vcc, v5, v1
	s_orn2_b64 s[16:17], vcc, exec
	s_branch .LBB0_92

; __device__ __forceinline__ unsigned xb_ld(unsigned* p)              { return __hip_atomic_load(p, __ATOMIC_RELAXED, __HIP_MEMORY_SCOPE_AGENT); }
; __device__ __forceinline__ unsigned xb_add(unsigned* p, unsigned v) { return __hip_atomic_fetch_add(p, v, __ATOMIC_RELAXED, __HIP_MEMORY_SCOPE_AGENT); }
; #define XB_SPIN(cond, bar) do { unsigned _sp = 0; while (cond) { __builtin_amdgcn_s_sleep(1); \
;     if ((++_sp & 255u) == 0u) { if (xb_ld(&(bar)[XB_TMO])) break; if (_sp > XB_SPIN_CAP) { atomicAdd(&(bar)[XB_TMO], 1u); break; } } } } while (0)
; __device__ __forceinline__ void xcd_barrier(const XcdBarrier& b) {
;     ...
;         const unsigned old = xb_add(&bar[XB_XSUB(b.x)], 1u);
;         const unsigned gen = old / nloc;
;         if (old + 1u == (gen + 1u) * nloc) {
;             __builtin_amdgcn_fence(__ATOMIC_RELEASE, "agent");
;             asm volatile("s_waitcnt vmcnt(0)" ::: "memory");
;             const unsigned og = xb_add(&bar[XB_TOP], 1u);
;             const unsigned tg = og / nx;
;             if (og + 1u == (tg + 1u) * nx) xb_add(&bar[XB_TOPGEN], 1u);
;             else XB_SPIN(xb_ld(&bar[XB_TOPGEN]) == tg, bar);
;             __builtin_amdgcn_fence(__ATOMIC_ACQUIRE, "agent");
;             xb_add(&bar[XB_XGEN(b.x)], 1u);
;             asm volatile("s_waitcnt vmcnt(0)" ::: "memory");
;         } else {
;             XB_SPIN(xb_ld(&bar[XB_XGEN(b.x)]) == gen, bar);
;             __builtin_amdgcn_fence(__ATOMIC_ACQUIRE, "agent");
.LBB0_242:
	s_or_b64 exec, exec, s[12:13]
	v_cvt_f32_u32_e32 v4, v2
	s_waitcnt vmcnt(0)
	v_readfirstlane_b32 s0, v3
	v_sub_u32_e32 v3, 0, v2
	v_rcp_iflag_f32_e32 v4, v4
	v_add_u32_e32 v5, s0, v1
	v_mul_f32_e32 v4, 0x4f7ffffe, v4
	v_cvt_u32_f32_e32 v4, v4
	v_mul_lo_u32 v1, v3, v4
	v_mul_hi_u32 v1, v4, v1
	v_add_u32_e32 v1, v4, v1
	v_mul_hi_u32 v1, v5, v1
	v_mul_lo_u32 v3, v1, v2
	v_sub_u32_e32 v3, v5, v3
	v_add_u32_e32 v4, 1, v1
	v_cmp_ge_u32_e32 vcc, v3, v2
	s_nop 1
	v_cndmask_b32_e32 v1, v1, v4, vcc
	v_sub_u32_e32 v4, v3, v2
	v_cndmask_b32_e32 v3, v3, v4, vcc
	v_add_u32_e32 v4, 1, v1
	v_cmp_ge_u32_e32 vcc, v3, v2
	v_add_u32_e32 v3, 1, v5
	s_nop 0
	v_cndmask_b32_e32 v1, v1, v4, vcc
	v_mul_lo_u32 v4, v2, v1
	v_add_u32_e32 v2, v4, v2
	v_cmp_ne_u32_e32 vcc, v3, v2
	s_and_saveexec_b64 s[12:13], vcc
	s_xor_b64 s[12:13], exec, s[12:13]
	s_cbranch_execz .LBB0_256
	v_readlane_b32 s24, v253, 0
	v_readlane_b32 s25, v253, 1
	s_waitcnt lgkmcnt(0)
	v_mul_lo_u32 v5, v1, v0
	v_add_u32_e32 v5, v5, v0
	s_nop 3
	buffer_inv sc1
	global_load_dword v0, v185, s[24:25] sc1
	s_waitcnt vmcnt(0)
	v_cmp_gt_u32_e32 vcc, v5, v0
	s_and_saveexec_b64 s[24:25], vcc
	s_cbranch_execz .LBB0_255
	s_mov_b32 s0, 1
	s_mov_b64 s[26:27], 0
	s_branch .LBB0_246

; __device__ __forceinline__ unsigned xb_ld(unsigned* p)              { return __hip_atomic_load(p, __ATOMIC_RELAXED, __HIP_MEMORY_SCOPE_AGENT); }
; #define XB_SPIN(cond, bar) do { unsigned _sp = 0; while (cond) { __builtin_amdgcn_s_sleep(1); \
;     if ((++_sp & 255u) == 0u) { if (xb_ld(&(bar)[XB_TMO])) break; if (_sp > XB_SPIN_CAP) { atomicAdd(&(bar)[XB_TMO], 1u); break; } } } } while (0)
; __device__ __forceinline__ void xcd_barrier(const XcdBarrier& b) {
;     ...
;             XB_SPIN(xb_ld(&bar[XB_XGEN(b.x)]) == gen, bar);
.LBB0_250:
	v_readlane_b32 s36, v253, 0
	v_readlane_b32 s37, v253, 1
	s_add_i32 s0, s0, 1
	s_mov_b64 s[38:39], -1
	s_nop 2
	global_load_dword v0, v185, s[36:37] sc1
	s_waitcnt vmcnt(0)
	v_cmp_le_u32_e32 vcc, v5, v0
	s_orn2_b64 s[36:37], vcc, exec
	s_branch .LBB0_245

; __device__ __forceinline__ unsigned xb_ld(unsigned* p)              { return __hip_atomic_load(p, __ATOMIC_RELAXED, __HIP_MEMORY_SCOPE_AGENT); }
; __device__ __forceinline__ unsigned xb_add(unsigned* p, unsigned v) { return __hip_atomic_fetch_add(p, v, __ATOMIC_RELAXED, __HIP_MEMORY_SCOPE_AGENT); }
; #define XB_SPIN(cond, bar) do { unsigned _sp = 0; while (cond) { __builtin_amdgcn_s_sleep(1); \
;     if ((++_sp & 255u) == 0u) { if (xb_ld(&(bar)[XB_TMO])) break; if (_sp > XB_SPIN_CAP) { atomicAdd(&(bar)[XB_TMO], 1u); break; } } } } while (0)
; __device__ __forceinline__ void xcd_barrier(const XcdBarrier& b) {
;     ...
;             const unsigned og = xb_add(&bar[XB_TOP], 1u);
;             const unsigned tg = og / nx;
;             if (og + 1u == (tg + 1u) * nx) xb_add(&bar[XB_TOPGEN], 1u);
;             else XB_SPIN(xb_ld(&bar[XB_TOPGEN]) == tg, bar);
.LBB0_259:
	s_or_b64 exec, exec, s[24:25]
	s_waitcnt vmcnt(0)
	v_readfirstlane_b32 s0, v2
	v_cvt_f32_u32_e32 v2, v0
	v_sub_u32_e32 v3, 0, v0
	v_add_u32_e32 v1, s0, v1
	v_readlane_b32 s12, v253, 2
	v_rcp_iflag_f32_e32 v2, v2
	v_readlane_b32 s13, v253, 3
	s_mov_b64 s[24:25], -1
	v_mul_f32_e32 v2, 0x4f7ffffe, v2
	v_cvt_u32_f32_e32 v2, v2
	v_mul_lo_u32 v3, v3, v2
	v_mul_hi_u32 v3, v2, v3
	v_add_u32_e32 v2, v2, v3
	v_mul_hi_u32 v2, v1, v2
	v_mul_lo_u32 v3, v2, v0
	v_sub_u32_e32 v3, v1, v3
	v_cmp_ge_u32_e32 vcc, v3, v0
	v_add_u32_e32 v4, 1, v2
	v_add_u32_e32 v1, 1, v1
	v_cndmask_b32_e32 v2, v2, v4, vcc
	v_sub_u32_e32 v4, v3, v0
	v_cndmask_b32_e32 v3, v3, v4, vcc
	v_cmp_ge_u32_e32 vcc, v3, v0
	v_add_u32_e32 v3, 1, v2
	s_nop 0
	v_cndmask_b32_e32 v2, v2, v3, vcc
	v_mul_lo_u32 v3, v0, v2
	v_add_u32_e32 v0, v3, v0
	v_cmp_ne_u32_e32 vcc, v1, v0
	v_mov_b32_e32 v5, v0
	v_mov_b64_e32 v[0:1], s[12:13]
	s_and_saveexec_b64 s[12:13], vcc
	s_cbranch_execz .LBB0_271
	v_readlane_b32 s24, v253, 0
	v_readlane_b32 s25, v253, 1
	s_mov_b64 s[26:27], 0
	s_nop 3
	global_load_dword v0, v185, s[24:25] sc1
	s_waitcnt vmcnt(0)
	v_cmp_gt_u32_e32 vcc, v5, v0
	s_and_saveexec_b64 s[24:25], vcc
	s_cbranch_execz .LBB0_270
	s_mov_b32 s0, 1
	s_branch .LBB0_263

; __device__ __forceinline__ unsigned xb_ld(unsigned* p)              { return __hip_atomic_load(p, __ATOMIC_RELAXED, __HIP_MEMORY_SCOPE_AGENT); }
; #define XB_SPIN(cond, bar) do { unsigned _sp = 0; while (cond) { __builtin_amdgcn_s_sleep(1); \
;     if ((++_sp & 255u) == 0u) { if (xb_ld(&(bar)[XB_TMO])) break; if (_sp > XB_SPIN_CAP) { atomicAdd(&(bar)[XB_TMO], 1u); break; } } } } while (0)
; __device__ __forceinline__ void xcd_barrier(const XcdBarrier& b) {
;     ...
;             XB_SPIN(xb_ld(&bar[XB_XGEN(b.x)]) == gen, bar);
.LBB0_1471:
	v_readlane_b32 s38, v253, 0
	v_readlane_b32 s39, v253, 1
	s_add_i32 s0, s0, 1
	s_mov_b64 s[40:41], -1
	s_nop 2
	global_load_dword v0, v185, s[38:39] sc1
	s_waitcnt vmcnt(0)
	v_cmp_le_u32_e32 vcc, v5, v0
	s_orn2_b64 s[38:39], vcc, exec
	s_branch .LBB0_1466
